# GEMM loops: LDS-DMA issue rebalanced 4/4/4/4 across the four load phases (A(1,0) staged in ph1, A(0,0) in ph3; waits 8/6/8/6)
# speedup vs baseline: 1.0179x; 1.0067x over previous
.LBB0_192:
	s_add_u32 s98, s14, 0xfff80000
	s_addc_u32 s99, s15, -1
	s_mov_b32 m0, s25
	s_nop 0
	global_load_lds_dwordx4 v136, s[98:99]
	s_mov_b32 m0, s26
	s_nop 0
	global_load_lds_dwordx4 v134, s[98:99]
	s_add_u32 s16, s14, 0xfff80080
	s_addc_u32 s17, s15, -1
	s_add_i32 s36, 0, 0x10000
	s_cmp_eq_u32 s35, 28
	s_cselect_b32 s19, s9, s17
	s_cselect_b32 s18, s30, s16
	s_cselect_b32 s17, s7, s34
	s_cselect_b32 s16, s31, s33
	s_add_i32 s38, 0, 0x14000
	ds_read_b128 v[138:141], v234
	ds_read_b128 v[146:149], v234 offset:1024
	ds_read_b128 v[162:165], v234 offset:2048
	ds_read_b128 v[166:169], v234 offset:3072
	ds_read_b128 v[170:173], v235
	ds_read_b128 v[174:177], v235 offset:1024
	ds_read_b128 v[178:181], v235 offset:2048
	ds_read_b128 v[182:185], v235 offset:3072
	s_add_i32 m0, s21, 0xc000
	ds_read_b128 v[186:189], v145
	ds_read_b128 v[190:193], v145 offset:1024
	ds_read_b128 v[194:197], v145 offset:2048
	ds_read_b128 v[198:201], v145 offset:3072
	ds_read_b128 v[202:205], v145 offset:4096
	ds_read_b128 v[214:217], v145 offset:5120
	ds_read_b128 v[218:221], v145 offset:6144
	ds_read_b128 v[222:225], v145 offset:7168
	global_load_lds_dwordx4 v136, s[14:15]
	s_add_i32 m0, s21, 0xe000
	s_nop 0
	global_load_lds_dwordx4 v134, s[14:15]
	s_waitcnt vmcnt(8)
	s_waitcnt lgkmcnt(0)
	s_barrier
	s_setprio 1
	s_waitcnt lgkmcnt(0)
	v_mfma_f32_16x16x32_bf16 v[124:127], v[138:141], v[186:189], v[124:127]
	v_mfma_f32_16x16x32_bf16 v[120:123], v[162:165], v[186:189], v[120:123]
	v_mfma_f32_16x16x32_bf16 v[116:119], v[138:141], v[194:197], v[116:119]
	v_mfma_f32_16x16x32_bf16 v[108:111], v[162:165], v[194:197], v[108:111]
	v_mfma_f32_16x16x32_bf16 v[100:103], v[138:141], v[202:205], v[100:103]
	v_mfma_f32_16x16x32_bf16 v[92:95], v[162:165], v[202:205], v[92:95]
	v_mfma_f32_16x16x32_bf16 v[84:87], v[138:141], v[218:221], v[84:87]
	v_mfma_f32_16x16x32_bf16 v[76:79], v[162:165], v[218:221], v[76:79]
	v_mfma_f32_16x16x32_bf16 v[124:127], v[146:149], v[190:193], v[124:127]
	v_mfma_f32_16x16x32_bf16 v[120:123], v[166:169], v[190:193], v[120:123]
	v_mfma_f32_16x16x32_bf16 v[116:119], v[146:149], v[198:201], v[116:119]
	v_mfma_f32_16x16x32_bf16 v[108:111], v[166:169], v[198:201], v[108:111]
	v_mfma_f32_16x16x32_bf16 v[100:103], v[146:149], v[214:217], v[100:103]
	v_mfma_f32_16x16x32_bf16 v[92:95], v[166:169], v[214:217], v[92:95]
	v_mfma_f32_16x16x32_bf16 v[84:87], v[146:149], v[222:225], v[84:87]
	v_mfma_f32_16x16x32_bf16 v[76:79], v[166:169], v[222:225], v[76:79]
	s_setprio 0
	s_setprio 1
	v_mfma_f32_16x16x32_bf16 v[112:115], v[170:173], v[186:189], v[112:115]
	v_mfma_f32_16x16x32_bf16 v[104:107], v[178:181], v[186:189], v[104:107]
	v_mfma_f32_16x16x32_bf16 v[96:99], v[170:173], v[194:197], v[96:99]
	v_mfma_f32_16x16x32_bf16 v[88:91], v[178:181], v[194:197], v[88:91]
	v_mfma_f32_16x16x32_bf16 v[80:83], v[170:173], v[202:205], v[80:83]
	v_mfma_f32_16x16x32_bf16 v[72:75], v[178:181], v[202:205], v[72:75]
	v_mfma_f32_16x16x32_bf16 v[68:71], v[170:173], v[218:221], v[68:71]
	v_mfma_f32_16x16x32_bf16 v[64:67], v[178:181], v[218:221], v[64:67]
	v_mfma_f32_16x16x32_bf16 v[112:115], v[174:177], v[190:193], v[112:115]
	v_mfma_f32_16x16x32_bf16 v[104:107], v[182:185], v[190:193], v[104:107]
	v_mfma_f32_16x16x32_bf16 v[96:99], v[174:177], v[198:201], v[96:99]
	v_mfma_f32_16x16x32_bf16 v[88:91], v[182:185], v[198:201], v[88:91]
	v_mfma_f32_16x16x32_bf16 v[80:83], v[174:177], v[214:217], v[80:83]
	v_mfma_f32_16x16x32_bf16 v[72:75], v[182:185], v[214:217], v[72:75]
	v_mfma_f32_16x16x32_bf16 v[68:71], v[174:177], v[222:225], v[68:71]
	v_mfma_f32_16x16x32_bf16 v[64:67], v[182:185], v[222:225], v[64:67]
	s_setprio 0
	s_barrier
	s_add_i32 s36, s36, s20
	s_add_u32 s100, s16, 0x80
	s_addc_u32 s101, s17, 0
	s_mov_b32 m0, s36
	ds_read_b128 v[186:189], v145 offset:16384
	ds_read_b128 v[190:193], v145 offset:17408
	ds_read_b128 v[194:197], v145 offset:18432
	ds_read_b128 v[198:201], v145 offset:19456
	ds_read_b128 v[202:205], v145 offset:20480
	ds_read_b128 v[214:217], v145 offset:21504
	ds_read_b128 v[218:221], v145 offset:22528
	ds_read_b128 v[222:225], v145 offset:23552
	global_load_lds_dwordx4 v152, s[16:17]
	s_add_i32 m0, s36, 0x2000
	s_add_u32 s36, s16, 0x80000
	s_addc_u32 s37, s17, 0
	s_add_i32 s38, s38, s20
	global_load_lds_dwordx4 v128, s[16:17]
	s_mov_b32 m0, s38
	s_nop 0
	global_load_lds_dwordx4 v152, s[36:37]
	s_add_i32 m0, s38, 0x2000
	s_nop 0
	global_load_lds_dwordx4 v128, s[36:37]
	s_waitcnt vmcnt(6)
	s_waitcnt lgkmcnt(0)
	s_barrier
	s_setprio 1
	s_waitcnt lgkmcnt(0)
	v_mfma_f32_16x16x32_bf16 v[60:63], v[138:141], v[186:189], v[60:63]
	v_mfma_f32_16x16x32_bf16 v[56:59], v[162:165], v[186:189], v[56:59]
	v_mfma_f32_16x16x32_bf16 v[52:55], v[138:141], v[194:197], v[52:55]
	v_mfma_f32_16x16x32_bf16 v[44:47], v[162:165], v[194:197], v[44:47]
	v_mfma_f32_16x16x32_bf16 v[36:39], v[138:141], v[202:205], v[36:39]
	v_mfma_f32_16x16x32_bf16 v[28:31], v[162:165], v[202:205], v[28:31]
	v_mfma_f32_16x16x32_bf16 v[20:23], v[138:141], v[218:221], v[20:23]
	v_mfma_f32_16x16x32_bf16 v[12:15], v[162:165], v[218:221], v[12:15]
	v_mfma_f32_16x16x32_bf16 v[60:63], v[146:149], v[190:193], v[60:63]
	v_mfma_f32_16x16x32_bf16 v[56:59], v[166:169], v[190:193], v[56:59]
	v_mfma_f32_16x16x32_bf16 v[52:55], v[146:149], v[198:201], v[52:55]
	v_mfma_f32_16x16x32_bf16 v[44:47], v[166:169], v[198:201], v[44:47]
	v_mfma_f32_16x16x32_bf16 v[36:39], v[146:149], v[214:217], v[36:39]
	v_mfma_f32_16x16x32_bf16 v[28:31], v[166:169], v[214:217], v[28:31]
	v_mfma_f32_16x16x32_bf16 v[20:23], v[146:149], v[222:225], v[20:23]
	v_mfma_f32_16x16x32_bf16 v[12:15], v[166:169], v[222:225], v[12:15]
	s_setprio 0
	s_setprio 1
	v_mfma_f32_16x16x32_bf16 v[48:51], v[170:173], v[186:189], v[48:51]
	v_mfma_f32_16x16x32_bf16 v[40:43], v[178:181], v[186:189], v[40:43]
	v_mfma_f32_16x16x32_bf16 v[32:35], v[170:173], v[194:197], v[32:35]
	v_mfma_f32_16x16x32_bf16 v[24:27], v[178:181], v[194:197], v[24:27]
	v_mfma_f32_16x16x32_bf16 v[16:19], v[170:173], v[202:205], v[16:19]
	v_mfma_f32_16x16x32_bf16 v[8:11], v[178:181], v[202:205], v[8:11]
	v_mfma_f32_16x16x32_bf16 v[4:7], v[170:173], v[218:221], v[4:7]
	v_mfma_f32_16x16x32_bf16 v[0:3], v[178:181], v[218:221], v[0:3]
	v_mfma_f32_16x16x32_bf16 v[48:51], v[174:177], v[190:193], v[48:51]
	v_mfma_f32_16x16x32_bf16 v[40:43], v[182:185], v[190:193], v[40:43]
	v_mfma_f32_16x16x32_bf16 v[32:35], v[174:177], v[198:201], v[32:35]
	v_mfma_f32_16x16x32_bf16 v[24:27], v[182:185], v[198:201], v[24:27]
	v_mfma_f32_16x16x32_bf16 v[16:19], v[174:177], v[214:217], v[16:19]
	v_mfma_f32_16x16x32_bf16 v[8:11], v[182:185], v[214:217], v[8:11]
	v_mfma_f32_16x16x32_bf16 v[4:7], v[174:177], v[222:225], v[4:7]
	v_mfma_f32_16x16x32_bf16 v[0:3], v[182:185], v[222:225], v[0:3]
	s_setprio 0
	s_barrier
	s_mov_b32 m0, s21
	s_nop 0
	global_load_lds_dwordx4 v132, s[18:19]
	s_mov_b32 m0, s22
	s_nop 0
	global_load_lds_dwordx4 v130, s[18:19]
	s_add_i32 s36, 0, 0x18000
	s_add_i32 s37, 0, 0x1c000
	ds_read_b128 v[138:141], v236
	ds_read_b128 v[146:149], v236 offset:1024
	ds_read_b128 v[162:165], v236 offset:2048
	ds_read_b128 v[166:169], v236 offset:3072
	ds_read_b128 v[170:173], v237
	ds_read_b128 v[174:177], v237 offset:1024
	ds_read_b128 v[178:181], v237 offset:2048
	ds_read_b128 v[182:185], v237 offset:3072
	s_add_u32 s18, s18, 0x80000
	s_addc_u32 s19, s19, 0
	s_mov_b32 m0, s23
	ds_read_b128 v[186:189], v145 offset:32768
	ds_read_b128 v[190:193], v145 offset:33792
	ds_read_b128 v[194:197], v145 offset:34816
	ds_read_b128 v[198:201], v145 offset:35840
	ds_read_b128 v[202:205], v145 offset:36864
	ds_read_b128 v[214:217], v145 offset:37888
	ds_read_b128 v[218:221], v145 offset:38912
	ds_read_b128 v[222:225], v145 offset:39936
	global_load_lds_dwordx4 v132, s[18:19]
	s_mov_b32 m0, s24
	s_nop 0
	global_load_lds_dwordx4 v130, s[18:19]
	s_waitcnt vmcnt(8)
	s_waitcnt lgkmcnt(0)
	s_barrier
	s_setprio 1
	s_waitcnt lgkmcnt(0)
	v_mfma_f32_16x16x32_bf16 v[124:127], v[138:141], v[186:189], v[124:127]
	v_mfma_f32_16x16x32_bf16 v[120:123], v[162:165], v[186:189], v[120:123]
	v_mfma_f32_16x16x32_bf16 v[116:119], v[138:141], v[194:197], v[116:119]
	v_mfma_f32_16x16x32_bf16 v[108:111], v[162:165], v[194:197], v[108:111]
	v_mfma_f32_16x16x32_bf16 v[100:103], v[138:141], v[202:205], v[100:103]
	v_mfma_f32_16x16x32_bf16 v[92:95], v[162:165], v[202:205], v[92:95]
	v_mfma_f32_16x16x32_bf16 v[84:87], v[138:141], v[218:221], v[84:87]
	v_mfma_f32_16x16x32_bf16 v[76:79], v[162:165], v[218:221], v[76:79]
	v_mfma_f32_16x16x32_bf16 v[124:127], v[146:149], v[190:193], v[124:127]
	v_mfma_f32_16x16x32_bf16 v[120:123], v[166:169], v[190:193], v[120:123]
	v_mfma_f32_16x16x32_bf16 v[116:119], v[146:149], v[198:201], v[116:119]
	v_mfma_f32_16x16x32_bf16 v[108:111], v[166:169], v[198:201], v[108:111]
	v_mfma_f32_16x16x32_bf16 v[100:103], v[146:149], v[214:217], v[100:103]
	v_mfma_f32_16x16x32_bf16 v[92:95], v[166:169], v[214:217], v[92:95]
	v_mfma_f32_16x16x32_bf16 v[84:87], v[146:149], v[222:225], v[84:87]
	v_mfma_f32_16x16x32_bf16 v[76:79], v[166:169], v[222:225], v[76:79]
	s_setprio 0
	s_setprio 1
	v_mfma_f32_16x16x32_bf16 v[112:115], v[170:173], v[186:189], v[112:115]
	v_mfma_f32_16x16x32_bf16 v[104:107], v[178:181], v[186:189], v[104:107]
	v_mfma_f32_16x16x32_bf16 v[96:99], v[170:173], v[194:197], v[96:99]
	v_mfma_f32_16x16x32_bf16 v[88:91], v[178:181], v[194:197], v[88:91]
	v_mfma_f32_16x16x32_bf16 v[80:83], v[170:173], v[202:205], v[80:83]
	v_mfma_f32_16x16x32_bf16 v[72:75], v[178:181], v[202:205], v[72:75]
	v_mfma_f32_16x16x32_bf16 v[68:71], v[170:173], v[218:221], v[68:71]
	v_mfma_f32_16x16x32_bf16 v[64:67], v[178:181], v[218:221], v[64:67]
	v_mfma_f32_16x16x32_bf16 v[112:115], v[174:177], v[190:193], v[112:115]
	v_mfma_f32_16x16x32_bf16 v[104:107], v[182:185], v[190:193], v[104:107]
	v_mfma_f32_16x16x32_bf16 v[96:99], v[174:177], v[198:201], v[96:99]
	v_mfma_f32_16x16x32_bf16 v[88:91], v[182:185], v[198:201], v[88:91]
	v_mfma_f32_16x16x32_bf16 v[80:83], v[174:177], v[214:217], v[80:83]
	v_mfma_f32_16x16x32_bf16 v[72:75], v[182:185], v[214:217], v[72:75]
	v_mfma_f32_16x16x32_bf16 v[68:71], v[174:177], v[222:225], v[68:71]
	v_mfma_f32_16x16x32_bf16 v[64:67], v[182:185], v[222:225], v[64:67]
	s_setprio 0
	s_barrier
	s_add_i32 s18, s36, s20
	s_mov_b32 m0, s18
	ds_read_b128 v[186:189], v145 offset:49152
	ds_read_b128 v[190:193], v145 offset:50176
	ds_read_b128 v[194:197], v145 offset:51200
	ds_read_b128 v[198:201], v145 offset:52224
	ds_read_b128 v[202:205], v145 offset:53248
	ds_read_b128 v[214:217], v145 offset:54272
	ds_read_b128 v[218:221], v145 offset:55296
	ds_read_b128 v[222:225], v145 offset:56320
	global_load_lds_dwordx4 v152, s[100:101]
	s_add_i32 m0, s18, 0x2000
	s_add_u32 s16, s16, 0x80080
	s_addc_u32 s17, s17, 0
	s_add_i32 s18, s37, s20
	global_load_lds_dwordx4 v128, s[100:101]
	s_mov_b32 m0, s18
	s_nop 0
	global_load_lds_dwordx4 v152, s[16:17]
	s_add_i32 m0, s18, 0x2000
	s_nop 0
	global_load_lds_dwordx4 v128, s[16:17]
	s_waitcnt vmcnt(6)
	s_waitcnt lgkmcnt(0)
	s_barrier
	s_setprio 1
	s_waitcnt lgkmcnt(0)
	v_mfma_f32_16x16x32_bf16 v[60:63], v[138:141], v[186:189], v[60:63]
	v_mfma_f32_16x16x32_bf16 v[56:59], v[162:165], v[186:189], v[56:59]
	v_mfma_f32_16x16x32_bf16 v[52:55], v[138:141], v[194:197], v[52:55]
	v_mfma_f32_16x16x32_bf16 v[44:47], v[162:165], v[194:197], v[44:47]
	v_mfma_f32_16x16x32_bf16 v[36:39], v[138:141], v[202:205], v[36:39]
	v_mfma_f32_16x16x32_bf16 v[28:31], v[162:165], v[202:205], v[28:31]
	v_mfma_f32_16x16x32_bf16 v[20:23], v[138:141], v[218:221], v[20:23]
	v_mfma_f32_16x16x32_bf16 v[12:15], v[162:165], v[218:221], v[12:15]
	v_mfma_f32_16x16x32_bf16 v[60:63], v[146:149], v[190:193], v[60:63]
	v_mfma_f32_16x16x32_bf16 v[56:59], v[166:169], v[190:193], v[56:59]
	v_mfma_f32_16x16x32_bf16 v[52:55], v[146:149], v[198:201], v[52:55]
	v_mfma_f32_16x16x32_bf16 v[44:47], v[166:169], v[198:201], v[44:47]
	v_mfma_f32_16x16x32_bf16 v[36:39], v[146:149], v[214:217], v[36:39]
	v_mfma_f32_16x16x32_bf16 v[28:31], v[166:169], v[214:217], v[28:31]
	v_mfma_f32_16x16x32_bf16 v[20:23], v[146:149], v[222:225], v[20:23]
	v_mfma_f32_16x16x32_bf16 v[12:15], v[166:169], v[222:225], v[12:15]
	s_setprio 0
	s_setprio 1
	v_mfma_f32_16x16x32_bf16 v[48:51], v[170:173], v[186:189], v[48:51]
	v_mfma_f32_16x16x32_bf16 v[40:43], v[178:181], v[186:189], v[40:43]
	v_mfma_f32_16x16x32_bf16 v[32:35], v[170:173], v[194:197], v[32:35]
	v_mfma_f32_16x16x32_bf16 v[24:27], v[178:181], v[194:197], v[24:27]
	v_mfma_f32_16x16x32_bf16 v[16:19], v[170:173], v[202:205], v[16:19]
	v_mfma_f32_16x16x32_bf16 v[8:11], v[178:181], v[202:205], v[8:11]
	v_mfma_f32_16x16x32_bf16 v[4:7], v[170:173], v[218:221], v[4:7]
	v_mfma_f32_16x16x32_bf16 v[0:3], v[178:181], v[218:221], v[0:3]
	v_mfma_f32_16x16x32_bf16 v[48:51], v[174:177], v[190:193], v[48:51]
	v_mfma_f32_16x16x32_bf16 v[40:43], v[182:185], v[190:193], v[40:43]
	v_mfma_f32_16x16x32_bf16 v[32:35], v[174:177], v[198:201], v[32:35]
	v_mfma_f32_16x16x32_bf16 v[24:27], v[182:185], v[198:201], v[24:27]
	v_mfma_f32_16x16x32_bf16 v[16:19], v[174:177], v[214:217], v[16:19]
	v_mfma_f32_16x16x32_bf16 v[8:11], v[182:185], v[214:217], v[8:11]
	v_mfma_f32_16x16x32_bf16 v[4:7], v[174:177], v[222:225], v[4:7]
	v_mfma_f32_16x16x32_bf16 v[0:3], v[182:185], v[222:225], v[0:3]
	s_setprio 0
	s_barrier
	s_add_i32 s35, s35, 2
	s_add_u32 s33, s33, 0x100
	s_addc_u32 s34, s34, 0
	s_add_u32 s14, s14, 0x100
	s_addc_u32 s15, s15, 0
	s_cmp_gt_u32 s35, 29
	s_cbranch_scc0 .LBB0_192
	s_and_b64 vcc, exec, s[4:5]
	s_cbranch_vccz .LBB0_195
	s_barrier

.LBB0_1383:
	s_add_u32 s98, s14, 0xfff80000
	s_addc_u32 s99, s15, -1
	s_mov_b32 m0, s27
	s_nop 0
	global_load_lds_dwordx4 v132, s[98:99]
	s_mov_b32 m0, s28
	s_nop 0
	global_load_lds_dwordx4 v130, s[98:99]
	s_add_u32 s16, s14, 0x100
	s_addc_u32 s17, s15, 0
	s_add_i32 s40, 0, 0x10000
	s_cmp_eq_u32 s37, 28
	s_cselect_b32 s21, s9, s17
	s_cselect_b32 s20, s33, s16
	s_cselect_b32 s19, s7, s36
	s_cselect_b32 s18, s34, s35
	s_add_i32 s41, 0, 0x14000
	ds_read_b128 v[134:137], v234
	ds_read_b128 v[144:147], v234 offset:1024
	ds_read_b128 v[148:151], v234 offset:2048
	ds_read_b128 v[162:165], v234 offset:3072
	ds_read_b128 v[166:169], v235
	ds_read_b128 v[170:173], v235 offset:1024
	ds_read_b128 v[174:177], v235 offset:2048
	ds_read_b128 v[178:181], v235 offset:3072
	s_add_i32 m0, s23, 0xc000
	ds_read_b128 v[182:185], v143
	ds_read_b128 v[186:189], v143 offset:1024
	ds_read_b128 v[190:193], v143 offset:2048
	ds_read_b128 v[194:197], v143 offset:3072
	ds_read_b128 v[198:201], v143 offset:4096
	ds_read_b128 v[202:205], v143 offset:5120
	ds_read_b128 v[214:217], v143 offset:6144
	ds_read_b128 v[218:221], v143 offset:7168
	global_load_lds_dwordx4 v132, s[14:15]
	s_add_i32 m0, s23, 0xe000
	s_nop 0
	global_load_lds_dwordx4 v130, s[14:15]
	s_waitcnt vmcnt(8)
	s_waitcnt lgkmcnt(0)
	s_barrier
	s_setprio 1
	s_waitcnt lgkmcnt(0)
	v_mfma_f32_16x16x32_bf16 v[124:127], v[134:137], v[182:185], v[124:127]
	v_mfma_f32_16x16x32_bf16 v[120:123], v[148:151], v[182:185], v[120:123]
	v_mfma_f32_16x16x32_bf16 v[108:111], v[134:137], v[190:193], v[108:111]
	v_mfma_f32_16x16x32_bf16 v[104:107], v[148:151], v[190:193], v[104:107]
	v_mfma_f32_16x16x32_bf16 v[92:95], v[134:137], v[198:201], v[92:95]
	v_mfma_f32_16x16x32_bf16 v[88:91], v[148:151], v[198:201], v[88:91]
	v_mfma_f32_16x16x32_bf16 v[76:79], v[134:137], v[214:217], v[76:79]
	v_mfma_f32_16x16x32_bf16 v[72:75], v[148:151], v[214:217], v[72:75]
	v_mfma_f32_16x16x32_bf16 v[124:127], v[144:147], v[186:189], v[124:127]
	v_mfma_f32_16x16x32_bf16 v[120:123], v[162:165], v[186:189], v[120:123]
	v_mfma_f32_16x16x32_bf16 v[108:111], v[144:147], v[194:197], v[108:111]
	v_mfma_f32_16x16x32_bf16 v[104:107], v[162:165], v[194:197], v[104:107]
	v_mfma_f32_16x16x32_bf16 v[92:95], v[144:147], v[202:205], v[92:95]
	v_mfma_f32_16x16x32_bf16 v[88:91], v[162:165], v[202:205], v[88:91]
	v_mfma_f32_16x16x32_bf16 v[76:79], v[144:147], v[218:221], v[76:79]
	v_mfma_f32_16x16x32_bf16 v[72:75], v[162:165], v[218:221], v[72:75]
	s_setprio 0
	s_setprio 1
	v_mfma_f32_16x16x32_bf16 v[116:119], v[166:169], v[182:185], v[116:119]
	v_mfma_f32_16x16x32_bf16 v[112:115], v[174:177], v[182:185], v[112:115]
	v_mfma_f32_16x16x32_bf16 v[100:103], v[166:169], v[190:193], v[100:103]
	v_mfma_f32_16x16x32_bf16 v[96:99], v[174:177], v[190:193], v[96:99]
	v_mfma_f32_16x16x32_bf16 v[84:87], v[166:169], v[198:201], v[84:87]
	v_mfma_f32_16x16x32_bf16 v[80:83], v[174:177], v[198:201], v[80:83]
	v_mfma_f32_16x16x32_bf16 v[68:71], v[166:169], v[214:217], v[68:71]
	v_mfma_f32_16x16x32_bf16 v[64:67], v[174:177], v[214:217], v[64:67]
	v_mfma_f32_16x16x32_bf16 v[116:119], v[170:173], v[186:189], v[116:119]
	v_mfma_f32_16x16x32_bf16 v[112:115], v[178:181], v[186:189], v[112:115]
	v_mfma_f32_16x16x32_bf16 v[100:103], v[170:173], v[194:197], v[100:103]
	v_mfma_f32_16x16x32_bf16 v[96:99], v[178:181], v[194:197], v[96:99]
	v_mfma_f32_16x16x32_bf16 v[84:87], v[170:173], v[202:205], v[84:87]
	v_mfma_f32_16x16x32_bf16 v[80:83], v[178:181], v[202:205], v[80:83]
	v_mfma_f32_16x16x32_bf16 v[68:71], v[170:173], v[218:221], v[68:71]
	v_mfma_f32_16x16x32_bf16 v[64:67], v[178:181], v[218:221], v[64:67]
	s_setprio 0
	s_barrier
	s_add_i32 s14, s40, s22
	s_add_u32 s100, s18, 0x80
	s_addc_u32 s101, s19, 0
	s_mov_b32 m0, s14
	ds_read_b128 v[182:185], v143 offset:16384
	ds_read_b128 v[186:189], v143 offset:17408
	ds_read_b128 v[190:193], v143 offset:18432
	ds_read_b128 v[194:197], v143 offset:19456
	ds_read_b128 v[198:201], v143 offset:20480
	ds_read_b128 v[202:205], v143 offset:21504
	ds_read_b128 v[214:217], v143 offset:22528
	ds_read_b128 v[218:221], v143 offset:23552
	global_load_lds_dwordx4 v152, s[18:19]
	s_add_i32 m0, s14, 0x2000
	s_add_u32 s14, s18, 0x80000
	s_addc_u32 s15, s19, 0
	s_add_i32 s40, s41, s22
	global_load_lds_dwordx4 v128, s[18:19]
	s_mov_b32 m0, s40
	s_nop 0
	global_load_lds_dwordx4 v152, s[14:15]
	s_add_i32 m0, s40, 0x2000
	s_nop 0
	global_load_lds_dwordx4 v128, s[14:15]
	s_waitcnt vmcnt(6)
	s_waitcnt lgkmcnt(0)
	s_barrier
	s_setprio 1
	s_waitcnt lgkmcnt(0)
	v_mfma_f32_16x16x32_bf16 v[60:63], v[134:137], v[182:185], v[60:63]
	v_mfma_f32_16x16x32_bf16 v[56:59], v[148:151], v[182:185], v[56:59]
	v_mfma_f32_16x16x32_bf16 v[44:47], v[134:137], v[190:193], v[44:47]
	v_mfma_f32_16x16x32_bf16 v[40:43], v[148:151], v[190:193], v[40:43]
	v_mfma_f32_16x16x32_bf16 v[28:31], v[134:137], v[198:201], v[28:31]
	v_mfma_f32_16x16x32_bf16 v[24:27], v[148:151], v[198:201], v[24:27]
	v_mfma_f32_16x16x32_bf16 v[12:15], v[134:137], v[214:217], v[12:15]
	v_mfma_f32_16x16x32_bf16 v[8:11], v[148:151], v[214:217], v[8:11]
	v_mfma_f32_16x16x32_bf16 v[60:63], v[144:147], v[186:189], v[60:63]
	v_mfma_f32_16x16x32_bf16 v[56:59], v[162:165], v[186:189], v[56:59]
	v_mfma_f32_16x16x32_bf16 v[44:47], v[144:147], v[194:197], v[44:47]
	v_mfma_f32_16x16x32_bf16 v[40:43], v[162:165], v[194:197], v[40:43]
	v_mfma_f32_16x16x32_bf16 v[28:31], v[144:147], v[202:205], v[28:31]
	v_mfma_f32_16x16x32_bf16 v[24:27], v[162:165], v[202:205], v[24:27]
	v_mfma_f32_16x16x32_bf16 v[12:15], v[144:147], v[218:221], v[12:15]
	v_mfma_f32_16x16x32_bf16 v[8:11], v[162:165], v[218:221], v[8:11]
	s_setprio 0
	s_setprio 1
	v_mfma_f32_16x16x32_bf16 v[52:55], v[166:169], v[182:185], v[52:55]
	v_mfma_f32_16x16x32_bf16 v[48:51], v[174:177], v[182:185], v[48:51]
	v_mfma_f32_16x16x32_bf16 v[36:39], v[166:169], v[190:193], v[36:39]
	v_mfma_f32_16x16x32_bf16 v[32:35], v[174:177], v[190:193], v[32:35]
	v_mfma_f32_16x16x32_bf16 v[20:23], v[166:169], v[198:201], v[20:23]
	v_mfma_f32_16x16x32_bf16 v[16:19], v[174:177], v[198:201], v[16:19]
	v_mfma_f32_16x16x32_bf16 v[4:7], v[166:169], v[214:217], v[4:7]
	v_mfma_f32_16x16x32_bf16 v[0:3], v[174:177], v[214:217], v[0:3]
	v_mfma_f32_16x16x32_bf16 v[52:55], v[170:173], v[186:189], v[52:55]
	v_mfma_f32_16x16x32_bf16 v[48:51], v[178:181], v[186:189], v[48:51]
	v_mfma_f32_16x16x32_bf16 v[36:39], v[170:173], v[194:197], v[36:39]
	v_mfma_f32_16x16x32_bf16 v[32:35], v[178:181], v[194:197], v[32:35]
	v_mfma_f32_16x16x32_bf16 v[20:23], v[170:173], v[202:205], v[20:23]
	v_mfma_f32_16x16x32_bf16 v[16:19], v[178:181], v[202:205], v[16:19]
	v_mfma_f32_16x16x32_bf16 v[4:7], v[170:173], v[218:221], v[4:7]
	v_mfma_f32_16x16x32_bf16 v[0:3], v[178:181], v[218:221], v[0:3]
	s_setprio 0
	s_barrier
	s_mov_b32 m0, s23
	s_nop 0
	global_load_lds_dwordx4 v152, s[20:21]
	s_mov_b32 m0, s24
	s_nop 0
	global_load_lds_dwordx4 v128, s[20:21]
	s_add_i32 s40, 0, 0x18000
	s_add_i32 s41, 0, 0x1c000
	ds_read_b128 v[134:137], v236
	ds_read_b128 v[144:147], v236 offset:1024
	ds_read_b128 v[148:151], v236 offset:2048
	ds_read_b128 v[162:165], v236 offset:3072
	ds_read_b128 v[166:169], v237
	ds_read_b128 v[170:173], v237 offset:1024
	ds_read_b128 v[174:177], v237 offset:2048
	ds_read_b128 v[178:181], v237 offset:3072
	s_add_u32 s14, s20, 0x80000
	s_addc_u32 s15, s21, 0
	s_mov_b32 m0, s25
	ds_read_b128 v[182:185], v143 offset:32768
	ds_read_b128 v[186:189], v143 offset:33792
	ds_read_b128 v[190:193], v143 offset:34816
	ds_read_b128 v[194:197], v143 offset:35840
	ds_read_b128 v[198:201], v143 offset:36864
	ds_read_b128 v[202:205], v143 offset:37888
	ds_read_b128 v[214:217], v143 offset:38912
	ds_read_b128 v[218:221], v143 offset:39936
	global_load_lds_dwordx4 v152, s[14:15]
	s_mov_b32 m0, s26
	s_nop 0
	global_load_lds_dwordx4 v128, s[14:15]
	s_waitcnt vmcnt(8)
	s_waitcnt lgkmcnt(0)
	s_barrier
	s_setprio 1
	s_waitcnt lgkmcnt(0)
	v_mfma_f32_16x16x32_bf16 v[124:127], v[134:137], v[182:185], v[124:127]
	v_mfma_f32_16x16x32_bf16 v[120:123], v[148:151], v[182:185], v[120:123]
	v_mfma_f32_16x16x32_bf16 v[108:111], v[134:137], v[190:193], v[108:111]
	v_mfma_f32_16x16x32_bf16 v[104:107], v[148:151], v[190:193], v[104:107]
	v_mfma_f32_16x16x32_bf16 v[92:95], v[134:137], v[198:201], v[92:95]
	v_mfma_f32_16x16x32_bf16 v[88:91], v[148:151], v[198:201], v[88:91]
	v_mfma_f32_16x16x32_bf16 v[76:79], v[134:137], v[214:217], v[76:79]
	v_mfma_f32_16x16x32_bf16 v[72:75], v[148:151], v[214:217], v[72:75]
	v_mfma_f32_16x16x32_bf16 v[124:127], v[144:147], v[186:189], v[124:127]
	v_mfma_f32_16x16x32_bf16 v[120:123], v[162:165], v[186:189], v[120:123]
	v_mfma_f32_16x16x32_bf16 v[108:111], v[144:147], v[194:197], v[108:111]
	v_mfma_f32_16x16x32_bf16 v[104:107], v[162:165], v[194:197], v[104:107]
	v_mfma_f32_16x16x32_bf16 v[92:95], v[144:147], v[202:205], v[92:95]
	v_mfma_f32_16x16x32_bf16 v[88:91], v[162:165], v[202:205], v[88:91]
	v_mfma_f32_16x16x32_bf16 v[76:79], v[144:147], v[218:221], v[76:79]
	v_mfma_f32_16x16x32_bf16 v[72:75], v[162:165], v[218:221], v[72:75]
	s_setprio 0
	s_setprio 1
	v_mfma_f32_16x16x32_bf16 v[116:119], v[166:169], v[182:185], v[116:119]
	v_mfma_f32_16x16x32_bf16 v[112:115], v[174:177], v[182:185], v[112:115]
	v_mfma_f32_16x16x32_bf16 v[100:103], v[166:169], v[190:193], v[100:103]
	v_mfma_f32_16x16x32_bf16 v[96:99], v[174:177], v[190:193], v[96:99]
	v_mfma_f32_16x16x32_bf16 v[84:87], v[166:169], v[198:201], v[84:87]
	v_mfma_f32_16x16x32_bf16 v[80:83], v[174:177], v[198:201], v[80:83]
	v_mfma_f32_16x16x32_bf16 v[68:71], v[166:169], v[214:217], v[68:71]
	v_mfma_f32_16x16x32_bf16 v[64:67], v[174:177], v[214:217], v[64:67]
	v_mfma_f32_16x16x32_bf16 v[116:119], v[170:173], v[186:189], v[116:119]
	v_mfma_f32_16x16x32_bf16 v[112:115], v[178:181], v[186:189], v[112:115]
	v_mfma_f32_16x16x32_bf16 v[100:103], v[170:173], v[194:197], v[100:103]
	v_mfma_f32_16x16x32_bf16 v[96:99], v[178:181], v[194:197], v[96:99]
	v_mfma_f32_16x16x32_bf16 v[84:87], v[170:173], v[202:205], v[84:87]
	v_mfma_f32_16x16x32_bf16 v[80:83], v[178:181], v[202:205], v[80:83]
	v_mfma_f32_16x16x32_bf16 v[68:71], v[170:173], v[218:221], v[68:71]
	v_mfma_f32_16x16x32_bf16 v[64:67], v[178:181], v[218:221], v[64:67]
	s_setprio 0
	s_barrier
	s_add_i32 s14, s40, s22
	s_mov_b32 m0, s14
	ds_read_b128 v[182:185], v143 offset:49152
	ds_read_b128 v[186:189], v143 offset:50176
	ds_read_b128 v[190:193], v143 offset:51200
	ds_read_b128 v[194:197], v143 offset:52224
	ds_read_b128 v[198:201], v143 offset:53248
	ds_read_b128 v[202:205], v143 offset:54272
	ds_read_b128 v[214:217], v143 offset:55296
	ds_read_b128 v[218:221], v143 offset:56320
	global_load_lds_dwordx4 v152, s[100:101]
	s_add_i32 m0, s14, 0x2000
	s_add_u32 s14, s18, 0x80080
	s_addc_u32 s15, s19, 0
	s_add_i32 s18, s41, s22
	global_load_lds_dwordx4 v128, s[100:101]
	s_mov_b32 m0, s18
	s_nop 0
	global_load_lds_dwordx4 v152, s[14:15]
	s_add_i32 m0, s18, 0x2000
	s_nop 0
	global_load_lds_dwordx4 v128, s[14:15]
	s_waitcnt vmcnt(6)
	s_waitcnt lgkmcnt(0)
	s_barrier
	s_setprio 1
	s_waitcnt lgkmcnt(0)
	v_mfma_f32_16x16x32_bf16 v[60:63], v[134:137], v[182:185], v[60:63]
	v_mfma_f32_16x16x32_bf16 v[56:59], v[148:151], v[182:185], v[56:59]
	v_mfma_f32_16x16x32_bf16 v[44:47], v[134:137], v[190:193], v[44:47]
	v_mfma_f32_16x16x32_bf16 v[40:43], v[148:151], v[190:193], v[40:43]
	v_mfma_f32_16x16x32_bf16 v[28:31], v[134:137], v[198:201], v[28:31]
	v_mfma_f32_16x16x32_bf16 v[24:27], v[148:151], v[198:201], v[24:27]
	v_mfma_f32_16x16x32_bf16 v[12:15], v[134:137], v[214:217], v[12:15]
	v_mfma_f32_16x16x32_bf16 v[8:11], v[148:151], v[214:217], v[8:11]
	v_mfma_f32_16x16x32_bf16 v[60:63], v[144:147], v[186:189], v[60:63]
	v_mfma_f32_16x16x32_bf16 v[56:59], v[162:165], v[186:189], v[56:59]
	v_mfma_f32_16x16x32_bf16 v[44:47], v[144:147], v[194:197], v[44:47]
	v_mfma_f32_16x16x32_bf16 v[40:43], v[162:165], v[194:197], v[40:43]
	v_mfma_f32_16x16x32_bf16 v[28:31], v[144:147], v[202:205], v[28:31]
	v_mfma_f32_16x16x32_bf16 v[24:27], v[162:165], v[202:205], v[24:27]
	v_mfma_f32_16x16x32_bf16 v[12:15], v[144:147], v[218:221], v[12:15]
	v_mfma_f32_16x16x32_bf16 v[8:11], v[162:165], v[218:221], v[8:11]
	s_setprio 0
	s_setprio 1
	v_mfma_f32_16x16x32_bf16 v[52:55], v[166:169], v[182:185], v[52:55]
	v_mfma_f32_16x16x32_bf16 v[48:51], v[174:177], v[182:185], v[48:51]
	v_mfma_f32_16x16x32_bf16 v[36:39], v[166:169], v[190:193], v[36:39]
	v_mfma_f32_16x16x32_bf16 v[32:35], v[174:177], v[190:193], v[32:35]
	v_mfma_f32_16x16x32_bf16 v[20:23], v[166:169], v[198:201], v[20:23]
	v_mfma_f32_16x16x32_bf16 v[16:19], v[174:177], v[198:201], v[16:19]
	v_mfma_f32_16x16x32_bf16 v[4:7], v[166:169], v[214:217], v[4:7]
	v_mfma_f32_16x16x32_bf16 v[0:3], v[174:177], v[214:217], v[0:3]
	v_mfma_f32_16x16x32_bf16 v[52:55], v[170:173], v[186:189], v[52:55]
	v_mfma_f32_16x16x32_bf16 v[48:51], v[178:181], v[186:189], v[48:51]
	v_mfma_f32_16x16x32_bf16 v[36:39], v[170:173], v[194:197], v[36:39]
	v_mfma_f32_16x16x32_bf16 v[32:35], v[178:181], v[194:197], v[32:35]
	v_mfma_f32_16x16x32_bf16 v[20:23], v[170:173], v[202:205], v[20:23]
	v_mfma_f32_16x16x32_bf16 v[16:19], v[178:181], v[202:205], v[16:19]
	v_mfma_f32_16x16x32_bf16 v[4:7], v[170:173], v[218:221], v[4:7]
	v_mfma_f32_16x16x32_bf16 v[0:3], v[178:181], v[218:221], v[0:3]
	s_setprio 0
	s_barrier
	s_add_i32 s37, s37, 2
	s_add_u32 s35, s35, 0x100
	s_addc_u32 s36, s36, 0
	s_cmp_gt_u32 s37, 29
	s_mov_b64 s[14:15], s[16:17]
	s_cbranch_scc0 .LBB0_1383
	s_and_b64 vcc, exec, s[4:5]
	s_cbranch_vccz .LBB0_1386
	s_barrier

.LBB0_1510:
	s_add_u32 s98, s14, 0xfff80000
	s_addc_u32 s99, s15, -1
	s_mov_b32 m0, s25
	s_nop 0
	global_load_lds_dwordx4 v136, s[98:99]
	s_mov_b32 m0, s26
	s_nop 0
	global_load_lds_dwordx4 v134, s[98:99]
	s_add_u32 s16, s14, 0xfff80080
	s_addc_u32 s17, s15, -1
	s_add_i32 s36, 0, 0x10000
	s_cmp_eq_u32 s35, 28
	s_cselect_b32 s19, s9, s17
	s_cselect_b32 s18, s30, s16
	s_cselect_b32 s17, s7, s34
	s_cselect_b32 s16, s31, s33
	s_add_i32 s40, 0, 0x14000
	ds_read_b128 v[144:147], v234
	ds_read_b128 v[148:151], v234 offset:1024
	ds_read_b128 v[162:165], v234 offset:2048
	ds_read_b128 v[166:169], v234 offset:3072
	ds_read_b128 v[170:173], v235
	ds_read_b128 v[174:177], v235 offset:1024
	ds_read_b128 v[178:181], v235 offset:2048
	ds_read_b128 v[182:185], v235 offset:3072
	s_add_i32 m0, s21, 0xc000
	ds_read_b128 v[186:189], v143
	ds_read_b128 v[190:193], v143 offset:1024
	ds_read_b128 v[194:197], v143 offset:2048
	ds_read_b128 v[198:201], v143 offset:3072
	ds_read_b128 v[202:205], v143 offset:4096
	ds_read_b128 v[214:217], v143 offset:5120
	ds_read_b128 v[218:221], v143 offset:6144
	ds_read_b128 v[222:225], v143 offset:7168
	global_load_lds_dwordx4 v136, s[14:15]
	s_add_i32 m0, s21, 0xe000
	s_nop 0
	global_load_lds_dwordx4 v134, s[14:15]
	s_waitcnt vmcnt(8)
	s_waitcnt lgkmcnt(0)
	s_barrier
	s_setprio 1
	s_waitcnt lgkmcnt(0)
	v_mfma_f32_16x16x32_bf16 v[124:127], v[144:147], v[186:189], v[124:127]
	v_mfma_f32_16x16x32_bf16 v[116:119], v[162:165], v[186:189], v[116:119]
	v_mfma_f32_16x16x32_bf16 v[108:111], v[144:147], v[194:197], v[108:111]
	v_mfma_f32_16x16x32_bf16 v[100:103], v[162:165], v[194:197], v[100:103]
	v_mfma_f32_16x16x32_bf16 v[92:95], v[144:147], v[202:205], v[92:95]
	v_mfma_f32_16x16x32_bf16 v[84:87], v[162:165], v[202:205], v[84:87]
	v_mfma_f32_16x16x32_bf16 v[76:79], v[144:147], v[218:221], v[76:79]
	v_mfma_f32_16x16x32_bf16 v[68:71], v[162:165], v[218:221], v[68:71]
	v_mfma_f32_16x16x32_bf16 v[124:127], v[148:151], v[190:193], v[124:127]
	v_mfma_f32_16x16x32_bf16 v[116:119], v[166:169], v[190:193], v[116:119]
	v_mfma_f32_16x16x32_bf16 v[108:111], v[148:151], v[198:201], v[108:111]
	v_mfma_f32_16x16x32_bf16 v[100:103], v[166:169], v[198:201], v[100:103]
	v_mfma_f32_16x16x32_bf16 v[92:95], v[148:151], v[214:217], v[92:95]
	v_mfma_f32_16x16x32_bf16 v[84:87], v[166:169], v[214:217], v[84:87]
	v_mfma_f32_16x16x32_bf16 v[76:79], v[148:151], v[222:225], v[76:79]
	v_mfma_f32_16x16x32_bf16 v[68:71], v[166:169], v[222:225], v[68:71]
	s_setprio 0
	s_setprio 1
	v_mfma_f32_16x16x32_bf16 v[120:123], v[170:173], v[186:189], v[120:123]
	v_mfma_f32_16x16x32_bf16 v[112:115], v[178:181], v[186:189], v[112:115]
	v_mfma_f32_16x16x32_bf16 v[104:107], v[170:173], v[194:197], v[104:107]
	v_mfma_f32_16x16x32_bf16 v[96:99], v[178:181], v[194:197], v[96:99]
	v_mfma_f32_16x16x32_bf16 v[88:91], v[170:173], v[202:205], v[88:91]
	v_mfma_f32_16x16x32_bf16 v[80:83], v[178:181], v[202:205], v[80:83]
	v_mfma_f32_16x16x32_bf16 v[72:75], v[170:173], v[218:221], v[72:75]
	v_mfma_f32_16x16x32_bf16 v[64:67], v[178:181], v[218:221], v[64:67]
	v_mfma_f32_16x16x32_bf16 v[120:123], v[174:177], v[190:193], v[120:123]
	v_mfma_f32_16x16x32_bf16 v[112:115], v[182:185], v[190:193], v[112:115]
	v_mfma_f32_16x16x32_bf16 v[104:107], v[174:177], v[198:201], v[104:107]
	v_mfma_f32_16x16x32_bf16 v[96:99], v[182:185], v[198:201], v[96:99]
	v_mfma_f32_16x16x32_bf16 v[88:91], v[174:177], v[214:217], v[88:91]
	v_mfma_f32_16x16x32_bf16 v[80:83], v[182:185], v[214:217], v[80:83]
	v_mfma_f32_16x16x32_bf16 v[72:75], v[174:177], v[222:225], v[72:75]
	v_mfma_f32_16x16x32_bf16 v[64:67], v[182:185], v[222:225], v[64:67]
	s_setprio 0
	s_barrier
	s_add_i32 s36, s36, s20
	s_add_u32 s100, s16, 0x80
	s_addc_u32 s101, s17, 0
	s_mov_b32 m0, s36
	ds_read_b128 v[186:189], v143 offset:16384
	ds_read_b128 v[190:193], v143 offset:17408
	ds_read_b128 v[194:197], v143 offset:18432
	ds_read_b128 v[198:201], v143 offset:19456
	ds_read_b128 v[202:205], v143 offset:20480
	ds_read_b128 v[214:217], v143 offset:21504
	ds_read_b128 v[218:221], v143 offset:22528
	ds_read_b128 v[222:225], v143 offset:23552
	global_load_lds_dwordx4 v152, s[16:17]
	s_add_i32 m0, s36, 0x2000
	s_add_u32 s36, s16, 0x80000
	s_addc_u32 s37, s17, 0
	s_add_i32 s40, s40, s20
	global_load_lds_dwordx4 v128, s[16:17]
	s_mov_b32 m0, s40
	s_nop 0
	global_load_lds_dwordx4 v152, s[36:37]
	s_add_i32 m0, s40, 0x2000
	s_nop 0
	global_load_lds_dwordx4 v128, s[36:37]
	s_waitcnt vmcnt(6)
	s_waitcnt lgkmcnt(0)
	s_barrier
	s_setprio 1
	s_waitcnt lgkmcnt(0)
	v_mfma_f32_16x16x32_bf16 v[60:63], v[144:147], v[186:189], v[60:63]
	v_mfma_f32_16x16x32_bf16 v[52:55], v[162:165], v[186:189], v[52:55]
	v_mfma_f32_16x16x32_bf16 v[44:47], v[144:147], v[194:197], v[44:47]
	v_mfma_f32_16x16x32_bf16 v[36:39], v[162:165], v[194:197], v[36:39]
	v_mfma_f32_16x16x32_bf16 v[28:31], v[144:147], v[202:205], v[28:31]
	v_mfma_f32_16x16x32_bf16 v[20:23], v[162:165], v[202:205], v[20:23]
	v_mfma_f32_16x16x32_bf16 v[12:15], v[144:147], v[218:221], v[12:15]
	v_mfma_f32_16x16x32_bf16 v[4:7], v[162:165], v[218:221], v[4:7]
	v_mfma_f32_16x16x32_bf16 v[60:63], v[148:151], v[190:193], v[60:63]
	v_mfma_f32_16x16x32_bf16 v[52:55], v[166:169], v[190:193], v[52:55]
	v_mfma_f32_16x16x32_bf16 v[44:47], v[148:151], v[198:201], v[44:47]
	v_mfma_f32_16x16x32_bf16 v[36:39], v[166:169], v[198:201], v[36:39]
	v_mfma_f32_16x16x32_bf16 v[28:31], v[148:151], v[214:217], v[28:31]
	v_mfma_f32_16x16x32_bf16 v[20:23], v[166:169], v[214:217], v[20:23]
	v_mfma_f32_16x16x32_bf16 v[12:15], v[148:151], v[222:225], v[12:15]
	v_mfma_f32_16x16x32_bf16 v[4:7], v[166:169], v[222:225], v[4:7]
	s_setprio 0
	s_setprio 1
	v_mfma_f32_16x16x32_bf16 v[56:59], v[170:173], v[186:189], v[56:59]
	v_mfma_f32_16x16x32_bf16 v[48:51], v[178:181], v[186:189], v[48:51]
	v_mfma_f32_16x16x32_bf16 v[40:43], v[170:173], v[194:197], v[40:43]
	v_mfma_f32_16x16x32_bf16 v[32:35], v[178:181], v[194:197], v[32:35]
	v_mfma_f32_16x16x32_bf16 v[24:27], v[170:173], v[202:205], v[24:27]
	v_mfma_f32_16x16x32_bf16 v[16:19], v[178:181], v[202:205], v[16:19]
	v_mfma_f32_16x16x32_bf16 v[8:11], v[170:173], v[218:221], v[8:11]
	v_mfma_f32_16x16x32_bf16 v[0:3], v[178:181], v[218:221], v[0:3]
	v_mfma_f32_16x16x32_bf16 v[56:59], v[174:177], v[190:193], v[56:59]
	v_mfma_f32_16x16x32_bf16 v[48:51], v[182:185], v[190:193], v[48:51]
	v_mfma_f32_16x16x32_bf16 v[40:43], v[174:177], v[198:201], v[40:43]
	v_mfma_f32_16x16x32_bf16 v[32:35], v[182:185], v[198:201], v[32:35]
	v_mfma_f32_16x16x32_bf16 v[24:27], v[174:177], v[214:217], v[24:27]
	v_mfma_f32_16x16x32_bf16 v[16:19], v[182:185], v[214:217], v[16:19]
	v_mfma_f32_16x16x32_bf16 v[8:11], v[174:177], v[222:225], v[8:11]
	v_mfma_f32_16x16x32_bf16 v[0:3], v[182:185], v[222:225], v[0:3]
	s_setprio 0
	s_barrier
	s_mov_b32 m0, s21
	s_nop 0
	global_load_lds_dwordx4 v132, s[18:19]
	s_mov_b32 m0, s22
	s_nop 0
	global_load_lds_dwordx4 v130, s[18:19]
	s_add_i32 s36, 0, 0x18000
	s_add_i32 s37, 0, 0x1c000
	ds_read_b128 v[144:147], v236
	ds_read_b128 v[148:151], v236 offset:1024
	ds_read_b128 v[162:165], v236 offset:2048
	ds_read_b128 v[166:169], v236 offset:3072
	ds_read_b128 v[170:173], v237
	ds_read_b128 v[174:177], v237 offset:1024
	ds_read_b128 v[178:181], v237 offset:2048
	ds_read_b128 v[182:185], v237 offset:3072
	s_add_u32 s18, s18, 0x80000
	s_addc_u32 s19, s19, 0
	s_mov_b32 m0, s23
	ds_read_b128 v[186:189], v143 offset:32768
	ds_read_b128 v[190:193], v143 offset:33792
	ds_read_b128 v[194:197], v143 offset:34816
	ds_read_b128 v[198:201], v143 offset:35840
	ds_read_b128 v[202:205], v143 offset:36864
	ds_read_b128 v[214:217], v143 offset:37888
	ds_read_b128 v[218:221], v143 offset:38912
	ds_read_b128 v[222:225], v143 offset:39936
	global_load_lds_dwordx4 v132, s[18:19]
	s_mov_b32 m0, s24
	s_nop 0
	global_load_lds_dwordx4 v130, s[18:19]
	s_waitcnt vmcnt(8)
	s_waitcnt lgkmcnt(0)
	s_barrier
	s_setprio 1
	s_waitcnt lgkmcnt(0)
	v_mfma_f32_16x16x32_bf16 v[124:127], v[144:147], v[186:189], v[124:127]
	v_mfma_f32_16x16x32_bf16 v[116:119], v[162:165], v[186:189], v[116:119]
	v_mfma_f32_16x16x32_bf16 v[108:111], v[144:147], v[194:197], v[108:111]
	v_mfma_f32_16x16x32_bf16 v[100:103], v[162:165], v[194:197], v[100:103]
	v_mfma_f32_16x16x32_bf16 v[92:95], v[144:147], v[202:205], v[92:95]
	v_mfma_f32_16x16x32_bf16 v[84:87], v[162:165], v[202:205], v[84:87]
	v_mfma_f32_16x16x32_bf16 v[76:79], v[144:147], v[218:221], v[76:79]
	v_mfma_f32_16x16x32_bf16 v[68:71], v[162:165], v[218:221], v[68:71]
	v_mfma_f32_16x16x32_bf16 v[124:127], v[148:151], v[190:193], v[124:127]
	v_mfma_f32_16x16x32_bf16 v[116:119], v[166:169], v[190:193], v[116:119]
	v_mfma_f32_16x16x32_bf16 v[108:111], v[148:151], v[198:201], v[108:111]
	v_mfma_f32_16x16x32_bf16 v[100:103], v[166:169], v[198:201], v[100:103]
	v_mfma_f32_16x16x32_bf16 v[92:95], v[148:151], v[214:217], v[92:95]
	v_mfma_f32_16x16x32_bf16 v[84:87], v[166:169], v[214:217], v[84:87]
	v_mfma_f32_16x16x32_bf16 v[76:79], v[148:151], v[222:225], v[76:79]
	v_mfma_f32_16x16x32_bf16 v[68:71], v[166:169], v[222:225], v[68:71]
	s_setprio 0
	s_setprio 1
	v_mfma_f32_16x16x32_bf16 v[120:123], v[170:173], v[186:189], v[120:123]
	v_mfma_f32_16x16x32_bf16 v[112:115], v[178:181], v[186:189], v[112:115]
	v_mfma_f32_16x16x32_bf16 v[104:107], v[170:173], v[194:197], v[104:107]
	v_mfma_f32_16x16x32_bf16 v[96:99], v[178:181], v[194:197], v[96:99]
	v_mfma_f32_16x16x32_bf16 v[88:91], v[170:173], v[202:205], v[88:91]
	v_mfma_f32_16x16x32_bf16 v[80:83], v[178:181], v[202:205], v[80:83]
	v_mfma_f32_16x16x32_bf16 v[72:75], v[170:173], v[218:221], v[72:75]
	v_mfma_f32_16x16x32_bf16 v[64:67], v[178:181], v[218:221], v[64:67]
	v_mfma_f32_16x16x32_bf16 v[120:123], v[174:177], v[190:193], v[120:123]
	v_mfma_f32_16x16x32_bf16 v[112:115], v[182:185], v[190:193], v[112:115]
	v_mfma_f32_16x16x32_bf16 v[104:107], v[174:177], v[198:201], v[104:107]
	v_mfma_f32_16x16x32_bf16 v[96:99], v[182:185], v[198:201], v[96:99]
	v_mfma_f32_16x16x32_bf16 v[88:91], v[174:177], v[214:217], v[88:91]
	v_mfma_f32_16x16x32_bf16 v[80:83], v[182:185], v[214:217], v[80:83]
	v_mfma_f32_16x16x32_bf16 v[72:75], v[174:177], v[222:225], v[72:75]
	v_mfma_f32_16x16x32_bf16 v[64:67], v[182:185], v[222:225], v[64:67]
	s_setprio 0
	s_barrier
	s_add_i32 s18, s36, s20
	s_mov_b32 m0, s18
	ds_read_b128 v[186:189], v143 offset:49152
	ds_read_b128 v[190:193], v143 offset:50176
	ds_read_b128 v[194:197], v143 offset:51200
	ds_read_b128 v[198:201], v143 offset:52224
	ds_read_b128 v[202:205], v143 offset:53248
	ds_read_b128 v[214:217], v143 offset:54272
	ds_read_b128 v[218:221], v143 offset:55296
	ds_read_b128 v[222:225], v143 offset:56320
	global_load_lds_dwordx4 v152, s[100:101]
	s_add_i32 m0, s18, 0x2000
	s_add_u32 s16, s16, 0x80080
	s_addc_u32 s17, s17, 0
	s_add_i32 s18, s37, s20
	global_load_lds_dwordx4 v128, s[100:101]
	s_mov_b32 m0, s18
	s_nop 0
	global_load_lds_dwordx4 v152, s[16:17]
	s_add_i32 m0, s18, 0x2000
	s_nop 0
	global_load_lds_dwordx4 v128, s[16:17]
	s_waitcnt vmcnt(6)
	s_waitcnt lgkmcnt(0)
	s_barrier
	s_setprio 1
	s_waitcnt lgkmcnt(0)
	v_mfma_f32_16x16x32_bf16 v[60:63], v[144:147], v[186:189], v[60:63]
	v_mfma_f32_16x16x32_bf16 v[52:55], v[162:165], v[186:189], v[52:55]
	v_mfma_f32_16x16x32_bf16 v[44:47], v[144:147], v[194:197], v[44:47]
	v_mfma_f32_16x16x32_bf16 v[36:39], v[162:165], v[194:197], v[36:39]
	v_mfma_f32_16x16x32_bf16 v[28:31], v[144:147], v[202:205], v[28:31]
	v_mfma_f32_16x16x32_bf16 v[20:23], v[162:165], v[202:205], v[20:23]
	v_mfma_f32_16x16x32_bf16 v[12:15], v[144:147], v[218:221], v[12:15]
	v_mfma_f32_16x16x32_bf16 v[4:7], v[162:165], v[218:221], v[4:7]
	v_mfma_f32_16x16x32_bf16 v[60:63], v[148:151], v[190:193], v[60:63]
	v_mfma_f32_16x16x32_bf16 v[52:55], v[166:169], v[190:193], v[52:55]
	v_mfma_f32_16x16x32_bf16 v[44:47], v[148:151], v[198:201], v[44:47]
	v_mfma_f32_16x16x32_bf16 v[36:39], v[166:169], v[198:201], v[36:39]
	v_mfma_f32_16x16x32_bf16 v[28:31], v[148:151], v[214:217], v[28:31]
	v_mfma_f32_16x16x32_bf16 v[20:23], v[166:169], v[214:217], v[20:23]
	v_mfma_f32_16x16x32_bf16 v[12:15], v[148:151], v[222:225], v[12:15]
	v_mfma_f32_16x16x32_bf16 v[4:7], v[166:169], v[222:225], v[4:7]
	s_setprio 0
	s_setprio 1
	v_mfma_f32_16x16x32_bf16 v[56:59], v[170:173], v[186:189], v[56:59]
	v_mfma_f32_16x16x32_bf16 v[48:51], v[178:181], v[186:189], v[48:51]
	v_mfma_f32_16x16x32_bf16 v[40:43], v[170:173], v[194:197], v[40:43]
	v_mfma_f32_16x16x32_bf16 v[32:35], v[178:181], v[194:197], v[32:35]
	v_mfma_f32_16x16x32_bf16 v[24:27], v[170:173], v[202:205], v[24:27]
	v_mfma_f32_16x16x32_bf16 v[16:19], v[178:181], v[202:205], v[16:19]
	v_mfma_f32_16x16x32_bf16 v[8:11], v[170:173], v[218:221], v[8:11]
	v_mfma_f32_16x16x32_bf16 v[0:3], v[178:181], v[218:221], v[0:3]
	v_mfma_f32_16x16x32_bf16 v[56:59], v[174:177], v[190:193], v[56:59]
	v_mfma_f32_16x16x32_bf16 v[48:51], v[182:185], v[190:193], v[48:51]
	v_mfma_f32_16x16x32_bf16 v[40:43], v[174:177], v[198:201], v[40:43]
	v_mfma_f32_16x16x32_bf16 v[32:35], v[182:185], v[198:201], v[32:35]
	v_mfma_f32_16x16x32_bf16 v[24:27], v[174:177], v[214:217], v[24:27]
	v_mfma_f32_16x16x32_bf16 v[16:19], v[182:185], v[214:217], v[16:19]
	v_mfma_f32_16x16x32_bf16 v[8:11], v[174:177], v[222:225], v[8:11]
	v_mfma_f32_16x16x32_bf16 v[0:3], v[182:185], v[222:225], v[0:3]
	s_setprio 0
	s_barrier
	s_add_i32 s35, s35, 2
	s_add_u32 s33, s33, 0x100
	s_addc_u32 s34, s34, 0
	s_add_u32 s14, s14, 0x100
	s_addc_u32 s15, s15, 0
	s_cmp_gt_u32 s35, 29
	s_cbranch_scc0 .LBB0_1510
	s_and_b64 vcc, exec, s[4:5]
	s_cbranch_vccz .LBB0_1513
	s_barrier

.LBB0_1590:
	s_add_u32 s98, s10, 0xffea0000
	s_addc_u32 s99, s11, -1
	s_mov_b32 m0, s23
	s_nop 0
	global_load_lds_dwordx4 v132, s[98:99]
	s_mov_b32 m0, s24
	s_nop 0
	global_load_lds_dwordx4 v130, s[98:99]
	s_add_u32 s12, s10, 0x100
	s_addc_u32 s13, s11, 0
	s_add_i32 s34, 0, 0x10000
	s_cmpk_eq_i32 s33, 0x54
	s_cselect_b32 s17, s3, s13
	s_cselect_b32 s16, s2, s12
	s_cselect_b32 s15, s9, s31
	s_cselect_b32 s14, s8, s30
	s_add_i32 s35, 0, 0x14000
	ds_read_b128 v[134:137], v234
	ds_read_b128 v[144:147], v234 offset:1024
	ds_read_b128 v[148:151], v234 offset:2048
	ds_read_b128 v[162:165], v234 offset:3072
	ds_read_b128 v[166:169], v235
	ds_read_b128 v[170:173], v235 offset:1024
	ds_read_b128 v[174:177], v235 offset:2048
	ds_read_b128 v[178:181], v235 offset:3072
	s_add_i32 m0, s19, 0xc000
	ds_read_b128 v[182:185], v143
	ds_read_b128 v[186:189], v143 offset:1024
	ds_read_b128 v[190:193], v143 offset:2048
	ds_read_b128 v[194:197], v143 offset:3072
	ds_read_b128 v[198:201], v143 offset:4096
	ds_read_b128 v[202:205], v143 offset:5120
	ds_read_b128 v[214:217], v143 offset:6144
	ds_read_b128 v[218:221], v143 offset:7168
	global_load_lds_dwordx4 v132, s[10:11]
	s_add_i32 m0, s19, 0xe000
	s_nop 0
	global_load_lds_dwordx4 v130, s[10:11]
	s_waitcnt vmcnt(8)
	s_waitcnt lgkmcnt(0)
	s_barrier
	s_setprio 1
	s_waitcnt lgkmcnt(0)
	v_mfma_f32_16x16x32_bf16 v[124:127], v[134:137], v[182:185], v[124:127]
	v_mfma_f32_16x16x32_bf16 v[120:123], v[148:151], v[182:185], v[120:123]
	v_mfma_f32_16x16x32_bf16 v[108:111], v[134:137], v[190:193], v[108:111]
	v_mfma_f32_16x16x32_bf16 v[104:107], v[148:151], v[190:193], v[104:107]
	v_mfma_f32_16x16x32_bf16 v[92:95], v[134:137], v[198:201], v[92:95]
	v_mfma_f32_16x16x32_bf16 v[88:91], v[148:151], v[198:201], v[88:91]
	v_mfma_f32_16x16x32_bf16 v[76:79], v[134:137], v[214:217], v[76:79]
	v_mfma_f32_16x16x32_bf16 v[72:75], v[148:151], v[214:217], v[72:75]
	v_mfma_f32_16x16x32_bf16 v[124:127], v[144:147], v[186:189], v[124:127]
	v_mfma_f32_16x16x32_bf16 v[120:123], v[162:165], v[186:189], v[120:123]
	v_mfma_f32_16x16x32_bf16 v[108:111], v[144:147], v[194:197], v[108:111]
	v_mfma_f32_16x16x32_bf16 v[104:107], v[162:165], v[194:197], v[104:107]
	v_mfma_f32_16x16x32_bf16 v[92:95], v[144:147], v[202:205], v[92:95]
	v_mfma_f32_16x16x32_bf16 v[88:91], v[162:165], v[202:205], v[88:91]
	v_mfma_f32_16x16x32_bf16 v[76:79], v[144:147], v[218:221], v[76:79]
	v_mfma_f32_16x16x32_bf16 v[72:75], v[162:165], v[218:221], v[72:75]
	s_setprio 0
	s_setprio 1
	v_mfma_f32_16x16x32_bf16 v[116:119], v[166:169], v[182:185], v[116:119]
	v_mfma_f32_16x16x32_bf16 v[112:115], v[174:177], v[182:185], v[112:115]
	v_mfma_f32_16x16x32_bf16 v[100:103], v[166:169], v[190:193], v[100:103]
	v_mfma_f32_16x16x32_bf16 v[96:99], v[174:177], v[190:193], v[96:99]
	v_mfma_f32_16x16x32_bf16 v[84:87], v[166:169], v[198:201], v[84:87]
	v_mfma_f32_16x16x32_bf16 v[80:83], v[174:177], v[198:201], v[80:83]
	v_mfma_f32_16x16x32_bf16 v[68:71], v[166:169], v[214:217], v[68:71]
	v_mfma_f32_16x16x32_bf16 v[64:67], v[174:177], v[214:217], v[64:67]
	v_mfma_f32_16x16x32_bf16 v[116:119], v[170:173], v[186:189], v[116:119]
	v_mfma_f32_16x16x32_bf16 v[112:115], v[178:181], v[186:189], v[112:115]
	v_mfma_f32_16x16x32_bf16 v[100:103], v[170:173], v[194:197], v[100:103]
	v_mfma_f32_16x16x32_bf16 v[96:99], v[178:181], v[194:197], v[96:99]
	v_mfma_f32_16x16x32_bf16 v[84:87], v[170:173], v[202:205], v[84:87]
	v_mfma_f32_16x16x32_bf16 v[80:83], v[178:181], v[202:205], v[80:83]
	v_mfma_f32_16x16x32_bf16 v[68:71], v[170:173], v[218:221], v[68:71]
	v_mfma_f32_16x16x32_bf16 v[64:67], v[178:181], v[218:221], v[64:67]
	s_setprio 0
	s_barrier
	s_add_i32 s10, s34, s18
	s_add_u32 s100, s14, 0x80
	s_addc_u32 s101, s15, 0
	s_mov_b32 m0, s10
	ds_read_b128 v[182:185], v143 offset:16384
	ds_read_b128 v[186:189], v143 offset:17408
	ds_read_b128 v[190:193], v143 offset:18432
	ds_read_b128 v[194:197], v143 offset:19456
	ds_read_b128 v[198:201], v143 offset:20480
	ds_read_b128 v[202:205], v143 offset:21504
	ds_read_b128 v[214:217], v143 offset:22528
	ds_read_b128 v[218:221], v143 offset:23552
	global_load_lds_dwordx4 v152, s[14:15]
	s_add_i32 m0, s10, 0x2000
	s_add_u32 s10, s14, 0x160000
	s_addc_u32 s11, s15, 0
	s_add_i32 s34, s35, s18
	global_load_lds_dwordx4 v128, s[14:15]
	s_mov_b32 m0, s34
	s_nop 0
	global_load_lds_dwordx4 v152, s[10:11]
	s_add_i32 m0, s34, 0x2000
	s_nop 0
	global_load_lds_dwordx4 v128, s[10:11]
	s_waitcnt vmcnt(6)
	s_waitcnt lgkmcnt(0)
	s_barrier
	s_setprio 1
	s_waitcnt lgkmcnt(0)
	v_mfma_f32_16x16x32_bf16 v[60:63], v[134:137], v[182:185], v[60:63]
	v_mfma_f32_16x16x32_bf16 v[56:59], v[148:151], v[182:185], v[56:59]
	v_mfma_f32_16x16x32_bf16 v[44:47], v[134:137], v[190:193], v[44:47]
	v_mfma_f32_16x16x32_bf16 v[40:43], v[148:151], v[190:193], v[40:43]
	v_mfma_f32_16x16x32_bf16 v[28:31], v[134:137], v[198:201], v[28:31]
	v_mfma_f32_16x16x32_bf16 v[24:27], v[148:151], v[198:201], v[24:27]
	v_mfma_f32_16x16x32_bf16 v[12:15], v[134:137], v[214:217], v[12:15]
	v_mfma_f32_16x16x32_bf16 v[8:11], v[148:151], v[214:217], v[8:11]
	v_mfma_f32_16x16x32_bf16 v[60:63], v[144:147], v[186:189], v[60:63]
	v_mfma_f32_16x16x32_bf16 v[56:59], v[162:165], v[186:189], v[56:59]
	v_mfma_f32_16x16x32_bf16 v[44:47], v[144:147], v[194:197], v[44:47]
	v_mfma_f32_16x16x32_bf16 v[40:43], v[162:165], v[194:197], v[40:43]
	v_mfma_f32_16x16x32_bf16 v[28:31], v[144:147], v[202:205], v[28:31]
	v_mfma_f32_16x16x32_bf16 v[24:27], v[162:165], v[202:205], v[24:27]
	v_mfma_f32_16x16x32_bf16 v[12:15], v[144:147], v[218:221], v[12:15]
	v_mfma_f32_16x16x32_bf16 v[8:11], v[162:165], v[218:221], v[8:11]
	s_setprio 0
	s_setprio 1
	v_mfma_f32_16x16x32_bf16 v[52:55], v[166:169], v[182:185], v[52:55]
	v_mfma_f32_16x16x32_bf16 v[48:51], v[174:177], v[182:185], v[48:51]
	v_mfma_f32_16x16x32_bf16 v[36:39], v[166:169], v[190:193], v[36:39]
	v_mfma_f32_16x16x32_bf16 v[32:35], v[174:177], v[190:193], v[32:35]
	v_mfma_f32_16x16x32_bf16 v[20:23], v[166:169], v[198:201], v[20:23]
	v_mfma_f32_16x16x32_bf16 v[16:19], v[174:177], v[198:201], v[16:19]
	v_mfma_f32_16x16x32_bf16 v[4:7], v[166:169], v[214:217], v[4:7]
	v_mfma_f32_16x16x32_bf16 v[0:3], v[174:177], v[214:217], v[0:3]
	v_mfma_f32_16x16x32_bf16 v[52:55], v[170:173], v[186:189], v[52:55]
	v_mfma_f32_16x16x32_bf16 v[48:51], v[178:181], v[186:189], v[48:51]
	v_mfma_f32_16x16x32_bf16 v[36:39], v[170:173], v[194:197], v[36:39]
	v_mfma_f32_16x16x32_bf16 v[32:35], v[178:181], v[194:197], v[32:35]
	v_mfma_f32_16x16x32_bf16 v[20:23], v[170:173], v[202:205], v[20:23]
	v_mfma_f32_16x16x32_bf16 v[16:19], v[178:181], v[202:205], v[16:19]
	v_mfma_f32_16x16x32_bf16 v[4:7], v[170:173], v[218:221], v[4:7]
	v_mfma_f32_16x16x32_bf16 v[0:3], v[178:181], v[218:221], v[0:3]
	s_setprio 0
	s_barrier
	s_mov_b32 m0, s19
	s_nop 0
	global_load_lds_dwordx4 v152, s[16:17]
	s_mov_b32 m0, s20
	s_nop 0
	global_load_lds_dwordx4 v128, s[16:17]
	s_add_i32 s34, 0, 0x18000
	s_add_i32 s35, 0, 0x1c000
	ds_read_b128 v[134:137], v236
	ds_read_b128 v[144:147], v236 offset:1024
	ds_read_b128 v[148:151], v236 offset:2048
	ds_read_b128 v[162:165], v236 offset:3072
	ds_read_b128 v[166:169], v237
	ds_read_b128 v[170:173], v237 offset:1024
	ds_read_b128 v[174:177], v237 offset:2048
	ds_read_b128 v[178:181], v237 offset:3072
	s_add_u32 s10, s16, 0x160000
	s_addc_u32 s11, s17, 0
	s_mov_b32 m0, s21
	ds_read_b128 v[182:185], v143 offset:32768
	ds_read_b128 v[186:189], v143 offset:33792
	ds_read_b128 v[190:193], v143 offset:34816
	ds_read_b128 v[194:197], v143 offset:35840
	ds_read_b128 v[198:201], v143 offset:36864
	ds_read_b128 v[202:205], v143 offset:37888
	ds_read_b128 v[214:217], v143 offset:38912
	ds_read_b128 v[218:221], v143 offset:39936
	global_load_lds_dwordx4 v152, s[10:11]
	s_mov_b32 m0, s22
	s_nop 0
	global_load_lds_dwordx4 v128, s[10:11]
	s_waitcnt vmcnt(8)
	s_waitcnt lgkmcnt(0)
	s_barrier
	s_setprio 1
	s_waitcnt lgkmcnt(0)
	v_mfma_f32_16x16x32_bf16 v[124:127], v[134:137], v[182:185], v[124:127]
	v_mfma_f32_16x16x32_bf16 v[120:123], v[148:151], v[182:185], v[120:123]
	v_mfma_f32_16x16x32_bf16 v[108:111], v[134:137], v[190:193], v[108:111]
	v_mfma_f32_16x16x32_bf16 v[104:107], v[148:151], v[190:193], v[104:107]
	v_mfma_f32_16x16x32_bf16 v[92:95], v[134:137], v[198:201], v[92:95]
	v_mfma_f32_16x16x32_bf16 v[88:91], v[148:151], v[198:201], v[88:91]
	v_mfma_f32_16x16x32_bf16 v[76:79], v[134:137], v[214:217], v[76:79]
	v_mfma_f32_16x16x32_bf16 v[72:75], v[148:151], v[214:217], v[72:75]
	v_mfma_f32_16x16x32_bf16 v[124:127], v[144:147], v[186:189], v[124:127]
	v_mfma_f32_16x16x32_bf16 v[120:123], v[162:165], v[186:189], v[120:123]
	v_mfma_f32_16x16x32_bf16 v[108:111], v[144:147], v[194:197], v[108:111]
	v_mfma_f32_16x16x32_bf16 v[104:107], v[162:165], v[194:197], v[104:107]
	v_mfma_f32_16x16x32_bf16 v[92:95], v[144:147], v[202:205], v[92:95]
	v_mfma_f32_16x16x32_bf16 v[88:91], v[162:165], v[202:205], v[88:91]
	v_mfma_f32_16x16x32_bf16 v[76:79], v[144:147], v[218:221], v[76:79]
	v_mfma_f32_16x16x32_bf16 v[72:75], v[162:165], v[218:221], v[72:75]
	s_setprio 0
	s_setprio 1
	v_mfma_f32_16x16x32_bf16 v[116:119], v[166:169], v[182:185], v[116:119]
	v_mfma_f32_16x16x32_bf16 v[112:115], v[174:177], v[182:185], v[112:115]
	v_mfma_f32_16x16x32_bf16 v[100:103], v[166:169], v[190:193], v[100:103]
	v_mfma_f32_16x16x32_bf16 v[96:99], v[174:177], v[190:193], v[96:99]
	v_mfma_f32_16x16x32_bf16 v[84:87], v[166:169], v[198:201], v[84:87]
	v_mfma_f32_16x16x32_bf16 v[80:83], v[174:177], v[198:201], v[80:83]
	v_mfma_f32_16x16x32_bf16 v[68:71], v[166:169], v[214:217], v[68:71]
	v_mfma_f32_16x16x32_bf16 v[64:67], v[174:177], v[214:217], v[64:67]
	v_mfma_f32_16x16x32_bf16 v[116:119], v[170:173], v[186:189], v[116:119]
	v_mfma_f32_16x16x32_bf16 v[112:115], v[178:181], v[186:189], v[112:115]
	v_mfma_f32_16x16x32_bf16 v[100:103], v[170:173], v[194:197], v[100:103]
	v_mfma_f32_16x16x32_bf16 v[96:99], v[178:181], v[194:197], v[96:99]
	v_mfma_f32_16x16x32_bf16 v[84:87], v[170:173], v[202:205], v[84:87]
	v_mfma_f32_16x16x32_bf16 v[80:83], v[178:181], v[202:205], v[80:83]
	v_mfma_f32_16x16x32_bf16 v[68:71], v[170:173], v[218:221], v[68:71]
	v_mfma_f32_16x16x32_bf16 v[64:67], v[178:181], v[218:221], v[64:67]
	s_setprio 0
	s_barrier
	s_add_i32 s10, s34, s18
	s_mov_b32 m0, s10
	ds_read_b128 v[182:185], v143 offset:49152
	ds_read_b128 v[186:189], v143 offset:50176
	ds_read_b128 v[190:193], v143 offset:51200
	ds_read_b128 v[194:197], v143 offset:52224
	ds_read_b128 v[198:201], v143 offset:53248
	ds_read_b128 v[202:205], v143 offset:54272
	ds_read_b128 v[214:217], v143 offset:55296
	ds_read_b128 v[218:221], v143 offset:56320
	global_load_lds_dwordx4 v152, s[100:101]
	s_add_i32 m0, s10, 0x2000
	s_add_u32 s10, s14, 0x160080
	s_addc_u32 s11, s15, 0
	s_add_i32 s14, s35, s18
	global_load_lds_dwordx4 v128, s[100:101]
	s_mov_b32 m0, s14
	s_nop 0
	global_load_lds_dwordx4 v152, s[10:11]
	s_add_i32 m0, s14, 0x2000
	s_nop 0
	global_load_lds_dwordx4 v128, s[10:11]
	s_waitcnt vmcnt(6)
	s_waitcnt lgkmcnt(0)
	s_barrier
	s_setprio 1
	s_waitcnt lgkmcnt(0)
	v_mfma_f32_16x16x32_bf16 v[60:63], v[134:137], v[182:185], v[60:63]
	v_mfma_f32_16x16x32_bf16 v[56:59], v[148:151], v[182:185], v[56:59]
	v_mfma_f32_16x16x32_bf16 v[44:47], v[134:137], v[190:193], v[44:47]
	v_mfma_f32_16x16x32_bf16 v[40:43], v[148:151], v[190:193], v[40:43]
	v_mfma_f32_16x16x32_bf16 v[28:31], v[134:137], v[198:201], v[28:31]
	v_mfma_f32_16x16x32_bf16 v[24:27], v[148:151], v[198:201], v[24:27]
	v_mfma_f32_16x16x32_bf16 v[12:15], v[134:137], v[214:217], v[12:15]
	v_mfma_f32_16x16x32_bf16 v[8:11], v[148:151], v[214:217], v[8:11]
	v_mfma_f32_16x16x32_bf16 v[60:63], v[144:147], v[186:189], v[60:63]
	v_mfma_f32_16x16x32_bf16 v[56:59], v[162:165], v[186:189], v[56:59]
	v_mfma_f32_16x16x32_bf16 v[44:47], v[144:147], v[194:197], v[44:47]
	v_mfma_f32_16x16x32_bf16 v[40:43], v[162:165], v[194:197], v[40:43]
	v_mfma_f32_16x16x32_bf16 v[28:31], v[144:147], v[202:205], v[28:31]
	v_mfma_f32_16x16x32_bf16 v[24:27], v[162:165], v[202:205], v[24:27]
	v_mfma_f32_16x16x32_bf16 v[12:15], v[144:147], v[218:221], v[12:15]
	v_mfma_f32_16x16x32_bf16 v[8:11], v[162:165], v[218:221], v[8:11]
	s_setprio 0
	s_setprio 1
	v_mfma_f32_16x16x32_bf16 v[52:55], v[166:169], v[182:185], v[52:55]
	v_mfma_f32_16x16x32_bf16 v[48:51], v[174:177], v[182:185], v[48:51]
	v_mfma_f32_16x16x32_bf16 v[36:39], v[166:169], v[190:193], v[36:39]
	v_mfma_f32_16x16x32_bf16 v[32:35], v[174:177], v[190:193], v[32:35]
	v_mfma_f32_16x16x32_bf16 v[20:23], v[166:169], v[198:201], v[20:23]
	v_mfma_f32_16x16x32_bf16 v[16:19], v[174:177], v[198:201], v[16:19]
	v_mfma_f32_16x16x32_bf16 v[4:7], v[166:169], v[214:217], v[4:7]
	v_mfma_f32_16x16x32_bf16 v[0:3], v[174:177], v[214:217], v[0:3]
	v_mfma_f32_16x16x32_bf16 v[52:55], v[170:173], v[186:189], v[52:55]
	v_mfma_f32_16x16x32_bf16 v[48:51], v[178:181], v[186:189], v[48:51]
	v_mfma_f32_16x16x32_bf16 v[36:39], v[170:173], v[194:197], v[36:39]
	v_mfma_f32_16x16x32_bf16 v[32:35], v[178:181], v[194:197], v[32:35]
	v_mfma_f32_16x16x32_bf16 v[20:23], v[170:173], v[202:205], v[20:23]
	v_mfma_f32_16x16x32_bf16 v[16:19], v[178:181], v[202:205], v[16:19]
	v_mfma_f32_16x16x32_bf16 v[4:7], v[170:173], v[218:221], v[4:7]
	v_mfma_f32_16x16x32_bf16 v[0:3], v[178:181], v[218:221], v[0:3]
	s_setprio 0
	s_barrier
	s_add_i32 s33, s33, 2
	s_add_u32 s30, s30, 0x100
	s_addc_u32 s31, s31, 0
	s_cmpk_gt_u32 s33, 0x55
	s_mov_b64 s[10:11], s[12:13]
	s_cbranch_scc0 .LBB0_1590
	s_and_b64 vcc, exec, s[6:7]
	s_cbranch_vccz .LBB0_1593
	s_barrier
